# D2 output stores without the nt hint (plain write-back stores)
# baseline (speedup 1.0000x reference)
;     __device__ __forceinline__ void operator()(const f32x4 (&acc)[2][2][4][2], const Unit& u, int wr, int wc, int fr, int fq) const {
;     ...
;             for (int m = 0; m < 4; ++m) {
;                 const int row = u.pm * BM + ai * HALF + wr * 64 + m * 16 + fr; float ss = 0.f; const float bsc = brow ? brow[row] : 1.0f;
; #pragma unroll
;                 for (int bj = 0; bj < 2; ++bj) { const size_t off = (size_t)row * 1024 + col0 + bj * HALF;
;                     f32x4 b0, b1;
;                     if (basef) { b0 = *(const f32x4*)(basef + off); b1 = *(const f32x4*)(basef + off + 4); }
;                     else { const u32x4 r = *(const u32x4*)(baseh + off);
;                         b0 = (f32x4){__uint_as_float(r.x << 16), __uint_as_float(r.x & 0xffff0000u), __uint_as_float(r.y << 16), __uint_as_float(r.y & 0xffff0000u)} * bsc;
;                         b1 = (f32x4){__uint_as_float(r.z << 16), __uint_as_float(r.z & 0xffff0000u), __uint_as_float(r.w << 16), __uint_as_float(r.w & 0xffff0000u)} * bsc; }
;                     const f32x4 o0 = b0 + acc[ai][bj][m][0] * scale, o1 = b1 + acc[ai][bj][m][1] * scale;
;                     if (out) { __builtin_nontemporal_store(o0, (f32x4*)(out + off)); __builtin_nontemporal_store(o1, (f32x4*)(out + off + 4)); }
.LBB0_1193:
	s_andn2_b64 vcc, exec, s[12:13]
	s_cbranch_vccnz .LBB0_1195
	v_lshl_add_u32 v146, s42, 8, v148
	v_lshl_or_b32 v144, s43, 8, v150
	v_ashrrev_i32_e32 v147, 31, v146
	v_ashrrev_i32_e32 v145, 31, v144
	v_lshlrev_b64 v[154:155], 10, v[146:147]
	v_lshl_add_u64 v[158:159], v[154:155], 0, v[144:145]
	v_lshlrev_b64 v[160:161], 1, v[158:159]
	v_lshl_add_u64 v[154:155], s[6:7], 0, v[160:161]
	global_load_dwordx4 v[154:157], v[154:155], off
	v_lshl_add_u64 v[158:159], v[158:159], 2, s[84:85]
	v_or_b32_e32 v160, 0x100, v160
	v_lshl_add_u64 v[160:161], s[6:7], 0, v[160:161]
	s_waitcnt vmcnt(0)
	v_lshlrev_b32_e32 v164, 16, v154
	v_and_b32_e32 v165, 0xffff0000, v154
	v_lshlrev_b32_e32 v154, 16, v155
	v_and_b32_e32 v155, 0xffff0000, v155
	v_lshlrev_b32_e32 v162, 16, v156
	v_and_b32_e32 v163, 0xffff0000, v156
	v_lshlrev_b32_e32 v156, 16, v157
	v_and_b32_e32 v157, 0xffff0000, v157
	v_pk_fma_f32 v[126:127], v[126:127], 0.5, v[154:155] op_sel_hi:[1,0,1]
	v_pk_fma_f32 v[124:125], v[124:125], 0.5, v[164:165] op_sel_hi:[1,0,1]
	v_pk_fma_f32 v[122:123], v[122:123], 0.5, v[156:157] op_sel_hi:[1,0,1]
	v_pk_fma_f32 v[120:121], v[120:121], 0.5, v[162:163] op_sel_hi:[1,0,1]
	global_store_dwordx4 v[158:159], v[124:127], off
	global_store_dwordx4 v[158:159], v[120:123], off offset:16
	global_load_dwordx4 v[120:123], v[160:161], off
	v_or_b32_e32 v124, 16, v146
	v_ashrrev_i32_e32 v125, 31, v124
	v_lshlrev_b64 v[124:125], 10, v[124:125]
	v_lshl_add_u64 v[124:125], v[124:125], 0, v[144:145]
	v_lshlrev_b64 v[126:127], 1, v[124:125]
	v_lshl_add_u64 v[154:155], s[6:7], 0, v[126:127]
	v_or_b32_e32 v126, 0x100, v126
	s_waitcnt vmcnt(0)
	v_lshlrev_b32_e32 v160, 16, v120
	v_and_b32_e32 v161, 0xffff0000, v120
	v_lshlrev_b32_e32 v120, 16, v121
	v_and_b32_e32 v121, 0xffff0000, v121
	v_lshlrev_b32_e32 v156, 16, v122
	v_and_b32_e32 v157, 0xffff0000, v122
	v_lshlrev_b32_e32 v122, 16, v123
	v_and_b32_e32 v123, 0xffff0000, v123
	v_pk_fma_f32 v[118:119], v[118:119], 0.5, v[120:121] op_sel_hi:[1,0,1]
	v_pk_fma_f32 v[116:117], v[116:117], 0.5, v[160:161] op_sel_hi:[1,0,1]
	v_pk_fma_f32 v[114:115], v[114:115], 0.5, v[122:123] op_sel_hi:[1,0,1]
	v_pk_fma_f32 v[112:113], v[112:113], 0.5, v[156:157] op_sel_hi:[1,0,1]
	global_store_dwordx4 v[158:159], v[116:119], off offset:512
	global_store_dwordx4 v[158:159], v[112:115], off offset:528
	global_load_dwordx4 v[112:115], v[154:155], off
	v_lshl_add_u64 v[116:117], v[124:125], 2, s[84:85]
	v_lshl_add_u64 v[118:119], s[6:7], 0, v[126:127]
	s_waitcnt vmcnt(0)
	v_lshlrev_b32_e32 v122, 16, v112
	v_and_b32_e32 v123, 0xffff0000, v112
	v_lshlrev_b32_e32 v112, 16, v113
	v_and_b32_e32 v113, 0xffff0000, v113
	v_lshlrev_b32_e32 v120, 16, v114
	v_and_b32_e32 v121, 0xffff0000, v114
	v_lshlrev_b32_e32 v114, 16, v115
	v_and_b32_e32 v115, 0xffff0000, v115
	v_pk_fma_f32 v[110:111], v[110:111], 0.5, v[112:113] op_sel_hi:[1,0,1]
	v_pk_fma_f32 v[108:109], v[108:109], 0.5, v[122:123] op_sel_hi:[1,0,1]
	v_pk_fma_f32 v[106:107], v[106:107], 0.5, v[114:115] op_sel_hi:[1,0,1]
	v_pk_fma_f32 v[104:105], v[104:105], 0.5, v[120:121] op_sel_hi:[1,0,1]
	global_store_dwordx4 v[116:117], v[108:111], off
	global_store_dwordx4 v[116:117], v[104:107], off offset:16
	global_load_dwordx4 v[104:107], v[118:119], off
	v_or_b32_e32 v108, 32, v146
	v_ashrrev_i32_e32 v109, 31, v108
	v_lshlrev_b64 v[108:109], 10, v[108:109]
	v_lshl_add_u64 v[108:109], v[108:109], 0, v[144:145]
	v_lshlrev_b64 v[110:111], 1, v[108:109]
	v_lshl_add_u64 v[112:113], s[6:7], 0, v[110:111]
	v_or_b32_e32 v110, 0x100, v110
	s_waitcnt vmcnt(0)
	v_lshlrev_b32_e32 v118, 16, v104
	v_and_b32_e32 v119, 0xffff0000, v104
	v_lshlrev_b32_e32 v104, 16, v105
	v_and_b32_e32 v105, 0xffff0000, v105
	v_lshlrev_b32_e32 v114, 16, v106
	v_and_b32_e32 v115, 0xffff0000, v106
	v_lshlrev_b32_e32 v106, 16, v107
	v_and_b32_e32 v107, 0xffff0000, v107
	v_pk_fma_f32 v[102:103], v[102:103], 0.5, v[104:105] op_sel_hi:[1,0,1]
	v_pk_fma_f32 v[100:101], v[100:101], 0.5, v[118:119] op_sel_hi:[1,0,1]
	v_pk_fma_f32 v[98:99], v[98:99], 0.5, v[106:107] op_sel_hi:[1,0,1]
	v_pk_fma_f32 v[96:97], v[96:97], 0.5, v[114:115] op_sel_hi:[1,0,1]
	global_store_dwordx4 v[116:117], v[100:103], off offset:512
	global_store_dwordx4 v[116:117], v[96:99], off offset:528
	global_load_dwordx4 v[96:99], v[112:113], off
	v_lshl_add_u64 v[100:101], v[108:109], 2, s[84:85]
	v_lshl_add_u64 v[102:103], s[6:7], 0, v[110:111]
	s_waitcnt vmcnt(0)
	v_lshlrev_b32_e32 v106, 16, v96
	v_and_b32_e32 v107, 0xffff0000, v96
	v_lshlrev_b32_e32 v96, 16, v97
	v_and_b32_e32 v97, 0xffff0000, v97
	v_lshlrev_b32_e32 v104, 16, v98
	v_and_b32_e32 v105, 0xffff0000, v98
	v_lshlrev_b32_e32 v98, 16, v99
	v_and_b32_e32 v99, 0xffff0000, v99
	v_pk_fma_f32 v[94:95], v[94:95], 0.5, v[96:97] op_sel_hi:[1,0,1]
	v_pk_fma_f32 v[92:93], v[92:93], 0.5, v[106:107] op_sel_hi:[1,0,1]
	v_pk_fma_f32 v[90:91], v[90:91], 0.5, v[98:99] op_sel_hi:[1,0,1]
	v_pk_fma_f32 v[88:89], v[88:89], 0.5, v[104:105] op_sel_hi:[1,0,1]
	global_store_dwordx4 v[100:101], v[92:95], off
	global_store_dwordx4 v[100:101], v[88:91], off offset:16
	global_load_dwordx4 v[88:91], v[102:103], off
	v_or_b32_e32 v92, 48, v146
	v_ashrrev_i32_e32 v93, 31, v92
	v_lshlrev_b64 v[92:93], 10, v[92:93]
	v_lshl_add_u64 v[92:93], v[92:93], 0, v[144:145]
	v_lshlrev_b64 v[94:95], 1, v[92:93]
	v_lshl_add_u64 v[96:97], s[6:7], 0, v[94:95]
	v_or_b32_e32 v94, 0x100, v94
	s_waitcnt vmcnt(0)
;     __device__ __forceinline__ void operator()(const f32x4 (&acc)[2][2][4][2], const Unit& u, int wr, int wc, int fr, int fq) const {
;     ...
;             for (int m = 0; m < 4; ++m) {
;                 const int row = u.pm * BM + ai * HALF + wr * 64 + m * 16 + fr; float ss = 0.f; const float bsc = brow ? brow[row] : 1.0f;
; #pragma unroll
;                 for (int bj = 0; bj < 2; ++bj) { const size_t off = (size_t)row * 1024 + col0 + bj * HALF;
;                     f32x4 b0, b1;
;                     if (basef) { b0 = *(const f32x4*)(basef + off); b1 = *(const f32x4*)(basef + off + 4); }
;                     else { const u32x4 r = *(const u32x4*)(baseh + off);
;                         b0 = (f32x4){__uint_as_float(r.x << 16), __uint_as_float(r.x & 0xffff0000u), __uint_as_float(r.y << 16), __uint_as_float(r.y & 0xffff0000u)} * bsc;
;                         b1 = (f32x4){__uint_as_float(r.z << 16), __uint_as_float(r.z & 0xffff0000u), __uint_as_float(r.w << 16), __uint_as_float(r.w & 0xffff0000u)} * bsc; }
;                     const f32x4 o0 = b0 + acc[ai][bj][m][0] * scale, o1 = b1 + acc[ai][bj][m][1] * scale;
;                     if (out) { __builtin_nontemporal_store(o0, (f32x4*)(out + off)); __builtin_nontemporal_store(o1, (f32x4*)(out + off + 4)); }
	v_lshlrev_b32_e32 v102, 16, v88
	v_and_b32_e32 v103, 0xffff0000, v88
	v_lshlrev_b32_e32 v88, 16, v89
	v_and_b32_e32 v89, 0xffff0000, v89
	v_lshlrev_b32_e32 v98, 16, v90
	v_and_b32_e32 v99, 0xffff0000, v90
	v_lshlrev_b32_e32 v90, 16, v91
	v_and_b32_e32 v91, 0xffff0000, v91
	v_pk_fma_f32 v[86:87], v[86:87], 0.5, v[88:89] op_sel_hi:[1,0,1]
	v_pk_fma_f32 v[84:85], v[84:85], 0.5, v[102:103] op_sel_hi:[1,0,1]
	v_pk_fma_f32 v[82:83], v[82:83], 0.5, v[90:91] op_sel_hi:[1,0,1]
	v_pk_fma_f32 v[80:81], v[80:81], 0.5, v[98:99] op_sel_hi:[1,0,1]
	global_store_dwordx4 v[100:101], v[84:87], off offset:512
	global_store_dwordx4 v[100:101], v[80:83], off offset:528
	global_load_dwordx4 v[80:83], v[96:97], off
	v_lshl_add_u64 v[84:85], v[92:93], 2, s[84:85]
	v_lshl_add_u64 v[86:87], s[6:7], 0, v[94:95]
	s_waitcnt vmcnt(0)
	v_lshlrev_b32_e32 v90, 16, v80
	v_and_b32_e32 v91, 0xffff0000, v80
	v_lshlrev_b32_e32 v80, 16, v81
	v_and_b32_e32 v81, 0xffff0000, v81
	v_lshlrev_b32_e32 v88, 16, v82
	v_and_b32_e32 v89, 0xffff0000, v82
	v_lshlrev_b32_e32 v82, 16, v83
	v_and_b32_e32 v83, 0xffff0000, v83
	v_pk_fma_f32 v[78:79], v[78:79], 0.5, v[80:81] op_sel_hi:[1,0,1]
	v_pk_fma_f32 v[76:77], v[76:77], 0.5, v[90:91] op_sel_hi:[1,0,1]
	v_pk_fma_f32 v[74:75], v[74:75], 0.5, v[82:83] op_sel_hi:[1,0,1]
	v_pk_fma_f32 v[72:73], v[72:73], 0.5, v[88:89] op_sel_hi:[1,0,1]
	global_store_dwordx4 v[84:85], v[76:79], off
	global_store_dwordx4 v[84:85], v[72:75], off offset:16
	global_load_dwordx4 v[72:75], v[86:87], off
	v_add_u32_e32 v76, 0x80, v146
	v_ashrrev_i32_e32 v77, 31, v76
	v_lshlrev_b64 v[76:77], 10, v[76:77]
	v_lshl_add_u64 v[76:77], v[76:77], 0, v[144:145]
	v_lshlrev_b64 v[78:79], 1, v[76:77]
	v_lshl_add_u64 v[80:81], s[6:7], 0, v[78:79]
	v_or_b32_e32 v78, 0x100, v78
	s_waitcnt vmcnt(0)
	v_lshlrev_b32_e32 v86, 16, v72
	v_and_b32_e32 v87, 0xffff0000, v72
	v_lshlrev_b32_e32 v72, 16, v73
	v_and_b32_e32 v73, 0xffff0000, v73
	v_lshlrev_b32_e32 v82, 16, v74
	v_and_b32_e32 v83, 0xffff0000, v74
	v_lshlrev_b32_e32 v74, 16, v75
	v_and_b32_e32 v75, 0xffff0000, v75
	v_pk_fma_f32 v[70:71], v[70:71], 0.5, v[72:73] op_sel_hi:[1,0,1]
	v_pk_fma_f32 v[68:69], v[68:69], 0.5, v[86:87] op_sel_hi:[1,0,1]
	v_pk_fma_f32 v[66:67], v[66:67], 0.5, v[74:75] op_sel_hi:[1,0,1]
	v_pk_fma_f32 v[64:65], v[64:65], 0.5, v[82:83] op_sel_hi:[1,0,1]
	global_store_dwordx4 v[84:85], v[68:71], off offset:512
	global_store_dwordx4 v[84:85], v[64:67], off offset:528
	global_load_dwordx4 v[64:67], v[80:81], off
	v_lshl_add_u64 v[68:69], v[76:77], 2, s[84:85]
	v_lshl_add_u64 v[70:71], s[6:7], 0, v[78:79]
	s_waitcnt vmcnt(0)
	v_lshlrev_b32_e32 v74, 16, v64
	v_and_b32_e32 v75, 0xffff0000, v64
	v_lshlrev_b32_e32 v64, 16, v65
	v_and_b32_e32 v65, 0xffff0000, v65
	v_lshlrev_b32_e32 v72, 16, v66
	v_and_b32_e32 v73, 0xffff0000, v66
	v_lshlrev_b32_e32 v66, 16, v67
	v_and_b32_e32 v67, 0xffff0000, v67
	v_pk_fma_f32 v[62:63], v[62:63], 0.5, v[64:65] op_sel_hi:[1,0,1]
	v_pk_fma_f32 v[60:61], v[60:61], 0.5, v[74:75] op_sel_hi:[1,0,1]
	v_pk_fma_f32 v[58:59], v[58:59], 0.5, v[66:67] op_sel_hi:[1,0,1]
	v_pk_fma_f32 v[56:57], v[56:57], 0.5, v[72:73] op_sel_hi:[1,0,1]
	global_store_dwordx4 v[68:69], v[60:63], off
	global_store_dwordx4 v[68:69], v[56:59], off offset:16
	global_load_dwordx4 v[56:59], v[70:71], off
	v_add_u32_e32 v60, 0x90, v146
	v_ashrrev_i32_e32 v61, 31, v60
	v_lshlrev_b64 v[60:61], 10, v[60:61]
	v_lshl_add_u64 v[60:61], v[60:61], 0, v[144:145]
	v_lshlrev_b64 v[62:63], 1, v[60:61]
	v_lshl_add_u64 v[64:65], s[6:7], 0, v[62:63]
	v_or_b32_e32 v62, 0x100, v62
	s_waitcnt vmcnt(0)
	v_lshlrev_b32_e32 v70, 16, v56
	v_and_b32_e32 v71, 0xffff0000, v56
	v_lshlrev_b32_e32 v56, 16, v57
	v_and_b32_e32 v57, 0xffff0000, v57
	v_lshlrev_b32_e32 v66, 16, v58
	v_and_b32_e32 v67, 0xffff0000, v58
	v_lshlrev_b32_e32 v58, 16, v59
	v_and_b32_e32 v59, 0xffff0000, v59
	v_pk_fma_f32 v[54:55], v[54:55], 0.5, v[56:57] op_sel_hi:[1,0,1]
	v_pk_fma_f32 v[52:53], v[52:53], 0.5, v[70:71] op_sel_hi:[1,0,1]
	v_pk_fma_f32 v[50:51], v[50:51], 0.5, v[58:59] op_sel_hi:[1,0,1]
	v_pk_fma_f32 v[48:49], v[48:49], 0.5, v[66:67] op_sel_hi:[1,0,1]
	global_store_dwordx4 v[68:69], v[52:55], off offset:512
	global_store_dwordx4 v[68:69], v[48:51], off offset:528
	global_load_dwordx4 v[48:51], v[64:65], off
	v_lshl_add_u64 v[52:53], v[60:61], 2, s[84:85]
	v_lshl_add_u64 v[54:55], s[6:7], 0, v[62:63]
	s_waitcnt vmcnt(0)
;     __device__ __forceinline__ void operator()(const f32x4 (&acc)[2][2][4][2], const Unit& u, int wr, int wc, int fr, int fq) const {
;     ...
;                 const int row = u.pm * BM + ai * HALF + wr * 64 + m * 16 + fr; float ss = 0.f; const float bsc = brow ? brow[row] : 1.0f;
; #pragma unroll
;                 for (int bj = 0; bj < 2; ++bj) { const size_t off = (size_t)row * 1024 + col0 + bj * HALF;
;                     f32x4 b0, b1;
;                     if (basef) { b0 = *(const f32x4*)(basef + off); b1 = *(const f32x4*)(basef + off + 4); }
;                     else { const u32x4 r = *(const u32x4*)(baseh + off);
;                         b0 = (f32x4){__uint_as_float(r.x << 16), __uint_as_float(r.x & 0xffff0000u), __uint_as_float(r.y << 16), __uint_as_float(r.y & 0xffff0000u)} * bsc;
;                         b1 = (f32x4){__uint_as_float(r.z << 16), __uint_as_float(r.z & 0xffff0000u), __uint_as_float(r.w << 16), __uint_as_float(r.w & 0xffff0000u)} * bsc; }
;                     const f32x4 o0 = b0 + acc[ai][bj][m][0] * scale, o1 = b1 + acc[ai][bj][m][1] * scale;
;                     if (out) { __builtin_nontemporal_store(o0, (f32x4*)(out + off)); __builtin_nontemporal_store(o1, (f32x4*)(out + off + 4)); }
	v_lshlrev_b32_e32 v58, 16, v48
	v_and_b32_e32 v59, 0xffff0000, v48
	v_lshlrev_b32_e32 v48, 16, v49
	v_and_b32_e32 v49, 0xffff0000, v49
	v_lshlrev_b32_e32 v56, 16, v50
	v_and_b32_e32 v57, 0xffff0000, v50
	v_lshlrev_b32_e32 v50, 16, v51
	v_and_b32_e32 v51, 0xffff0000, v51
	v_pk_fma_f32 v[46:47], v[46:47], 0.5, v[48:49] op_sel_hi:[1,0,1]
	v_pk_fma_f32 v[44:45], v[44:45], 0.5, v[58:59] op_sel_hi:[1,0,1]
	v_pk_fma_f32 v[42:43], v[42:43], 0.5, v[50:51] op_sel_hi:[1,0,1]
	v_pk_fma_f32 v[40:41], v[40:41], 0.5, v[56:57] op_sel_hi:[1,0,1]
	global_store_dwordx4 v[52:53], v[44:47], off
	global_store_dwordx4 v[52:53], v[40:43], off offset:16
	global_load_dwordx4 v[40:43], v[54:55], off
	v_add_u32_e32 v44, 0xa0, v146
	v_ashrrev_i32_e32 v45, 31, v44
	v_lshlrev_b64 v[44:45], 10, v[44:45]
	v_lshl_add_u64 v[44:45], v[44:45], 0, v[144:145]
	v_lshlrev_b64 v[46:47], 1, v[44:45]
	v_lshl_add_u64 v[48:49], s[6:7], 0, v[46:47]
	v_or_b32_e32 v46, 0x100, v46
	s_waitcnt vmcnt(0)
	v_lshlrev_b32_e32 v54, 16, v40
	v_and_b32_e32 v55, 0xffff0000, v40
	v_lshlrev_b32_e32 v40, 16, v41
	v_and_b32_e32 v41, 0xffff0000, v41
	v_lshlrev_b32_e32 v50, 16, v42
	v_and_b32_e32 v51, 0xffff0000, v42
	v_lshlrev_b32_e32 v42, 16, v43
	v_and_b32_e32 v43, 0xffff0000, v43
	v_pk_fma_f32 v[38:39], v[38:39], 0.5, v[40:41] op_sel_hi:[1,0,1]
	v_pk_fma_f32 v[36:37], v[36:37], 0.5, v[54:55] op_sel_hi:[1,0,1]
	v_pk_fma_f32 v[34:35], v[34:35], 0.5, v[42:43] op_sel_hi:[1,0,1]
	v_pk_fma_f32 v[32:33], v[32:33], 0.5, v[50:51] op_sel_hi:[1,0,1]
	global_store_dwordx4 v[52:53], v[36:39], off offset:512
	global_store_dwordx4 v[52:53], v[32:35], off offset:528
	global_load_dwordx4 v[32:35], v[48:49], off
	v_lshl_add_u64 v[36:37], v[44:45], 2, s[84:85]
	v_lshl_add_u64 v[38:39], s[6:7], 0, v[46:47]
	s_waitcnt vmcnt(0)
	v_lshlrev_b32_e32 v42, 16, v32
	v_and_b32_e32 v43, 0xffff0000, v32
	v_lshlrev_b32_e32 v32, 16, v33
	v_and_b32_e32 v33, 0xffff0000, v33
	v_lshlrev_b32_e32 v40, 16, v34
	v_and_b32_e32 v41, 0xffff0000, v34
	v_lshlrev_b32_e32 v34, 16, v35
	v_and_b32_e32 v35, 0xffff0000, v35
	v_pk_fma_f32 v[30:31], v[30:31], 0.5, v[32:33] op_sel_hi:[1,0,1]
	v_pk_fma_f32 v[28:29], v[28:29], 0.5, v[42:43] op_sel_hi:[1,0,1]
	v_pk_fma_f32 v[26:27], v[26:27], 0.5, v[34:35] op_sel_hi:[1,0,1]
	v_pk_fma_f32 v[24:25], v[24:25], 0.5, v[40:41] op_sel_hi:[1,0,1]
	global_store_dwordx4 v[36:37], v[28:31], off
	global_store_dwordx4 v[36:37], v[24:27], off offset:16
	global_load_dwordx4 v[24:27], v[38:39], off
	v_add_u32_e32 v28, 0xb0, v146
	v_ashrrev_i32_e32 v29, 31, v28
	v_lshlrev_b64 v[28:29], 10, v[28:29]
	v_lshl_add_u64 v[28:29], v[28:29], 0, v[144:145]
	v_lshlrev_b64 v[30:31], 1, v[28:29]
	v_lshl_add_u64 v[32:33], s[6:7], 0, v[30:31]
	v_or_b32_e32 v30, 0x100, v30
	s_waitcnt vmcnt(0)
	v_lshlrev_b32_e32 v38, 16, v24
	v_and_b32_e32 v39, 0xffff0000, v24
	v_lshlrev_b32_e32 v24, 16, v25
	v_and_b32_e32 v25, 0xffff0000, v25
	v_lshlrev_b32_e32 v34, 16, v26
	v_and_b32_e32 v35, 0xffff0000, v26
	v_lshlrev_b32_e32 v26, 16, v27
	v_and_b32_e32 v27, 0xffff0000, v27
	v_pk_fma_f32 v[22:23], v[22:23], 0.5, v[24:25] op_sel_hi:[1,0,1]
	v_pk_fma_f32 v[20:21], v[20:21], 0.5, v[38:39] op_sel_hi:[1,0,1]
	v_pk_fma_f32 v[18:19], v[18:19], 0.5, v[26:27] op_sel_hi:[1,0,1]
	v_pk_fma_f32 v[16:17], v[16:17], 0.5, v[34:35] op_sel_hi:[1,0,1]
	global_store_dwordx4 v[36:37], v[20:23], off offset:512
	global_store_dwordx4 v[36:37], v[16:19], off offset:528
	global_load_dwordx4 v[16:19], v[32:33], off
	v_lshl_add_u64 v[20:21], v[28:29], 2, s[84:85]
	v_lshl_add_u64 v[22:23], s[6:7], 0, v[30:31]
	s_waitcnt vmcnt(0)
	v_lshlrev_b32_e32 v26, 16, v16
	v_and_b32_e32 v27, 0xffff0000, v16
	v_lshlrev_b32_e32 v16, 16, v17
	v_and_b32_e32 v17, 0xffff0000, v17
	v_lshlrev_b32_e32 v24, 16, v18
	v_and_b32_e32 v25, 0xffff0000, v18
	v_lshlrev_b32_e32 v18, 16, v19
	v_and_b32_e32 v19, 0xffff0000, v19
	v_pk_fma_f32 v[14:15], v[14:15], 0.5, v[16:17] op_sel_hi:[1,0,1]
	v_pk_fma_f32 v[12:13], v[12:13], 0.5, v[26:27] op_sel_hi:[1,0,1]
	v_pk_fma_f32 v[10:11], v[10:11], 0.5, v[18:19] op_sel_hi:[1,0,1]
	v_pk_fma_f32 v[8:9], v[8:9], 0.5, v[24:25] op_sel_hi:[1,0,1]
	global_store_dwordx4 v[20:21], v[12:15], off
	global_store_dwordx4 v[20:21], v[8:11], off offset:16
	global_load_dwordx4 v[8:11], v[22:23], off
	s_waitcnt vmcnt(0)
	v_lshlrev_b32_e32 v14, 16, v8
	v_and_b32_e32 v15, 0xffff0000, v8
	v_lshlrev_b32_e32 v8, 16, v9
	v_and_b32_e32 v9, 0xffff0000, v9
	v_lshlrev_b32_e32 v12, 16, v10
	v_and_b32_e32 v13, 0xffff0000, v10
	v_lshlrev_b32_e32 v10, 16, v11
	v_and_b32_e32 v11, 0xffff0000, v11
	v_pk_fma_f32 v[6:7], v[6:7], 0.5, v[8:9] op_sel_hi:[1,0,1]
	v_pk_fma_f32 v[4:5], v[4:5], 0.5, v[14:15] op_sel_hi:[1,0,1]
	v_pk_fma_f32 v[2:3], v[2:3], 0.5, v[10:11] op_sel_hi:[1,0,1]
	v_pk_fma_f32 v[0:1], v[0:1], 0.5, v[12:13] op_sel_hi:[1,0,1]
	global_store_dwordx4 v[20:21], v[4:7], off offset:512
	global_store_dwordx4 v[20:21], v[0:3], off offset:528
